# P5 and P8 residual epilogues rewritten wide: permlane16 swaps, 16 dwordx4 loads in flight + 16 dwordx4 stores per wave instead of 32 serialized load-wait-store pairs; row sums via permlane swaps
# speedup vs baseline: 1.0303x; 1.0081x over previous
; __device__ __forceinline__ float bflo(unsigned w) { return __uint_as_float(w << 16); }
; __device__ __forceinline__ float bfhi(unsigned w) { return __uint_as_float(w & 0xffff0000u); }
; __device__ __forceinline__ unsigned pk2(float lo, float hi) { f32x2 v = {lo, hi}; bf16x2_t b = __builtin_convertvector(v, bf16x2_t); return __builtin_bit_cast(unsigned, b); }
;     template <int QPR> __device__ __forceinline__ void tailq(int row, int c, const f32x4 v, int) const { quad(row, c, v); }
;     template <int QPR> __device__ __forceinline__ void tailq(int row, int c, const f32x4 v, int) const { quad(row, c, v); }
;     __device__ __forceinline__ float quad(int row, int c, const f32x4 a) const {
;         bf16_t* xp = XB + (size_t)row * D + c;
;         const u32x2 xw = *(const u32x2*)xp;
;         const f32x4 x = (f32x4){bflo(xw.x), bfhi(xw.x), bflo(xw.y), bfhi(xw.y)} + a;
;         u32x2 w; w.x = pk2(x[0], x[1]); w.y = pk2(x[2], x[3]);
;         *(u32x2*)xp = w;
;         return (x[0] * x[0] + x[1] * x[1]) + (x[2] * x[2] + x[3] * x[3]); }
;     template <int QPR> __device__ __forceinline__ void tailq(int row, int c, const f32x4 v, int c0) const {
;         float sq = quad(row, c, v);
; #pragma unroll
;         for (int o = 1; o < QPR; o <<= 1) sq += __shfl_xor(sq, o);
;         if ((threadIdx.x & (QPR - 1)) == 0) ss[(size_t)row * 16 + (c0 >> 6)] = sq; }
;     __device__ __forceinline__ void operator()(const f32x4 (&acc)[2][2][4][2], const pg8::Unit& u, int wr, int wc, int fr, int fq) const {
;         const int row0 = u.pm * 256 + wr * 64 + fr, col0 = u.pn * 256 + wc * 32 + 4 * fq;
; #pragma unroll
;         for (int ai = 0; ai < 2; ++ai)
; #pragma unroll
;             for (int m = 0; m < 4; ++m) { const int row = row0 + ai * 128 + m * 16; float sq = 0.f;
; #pragma unroll
;                 for (int bj = 0; bj < 2; ++bj)
; #pragma unroll
;                     for (int n = 0; n < 2; ++n) { const int c = col0 + bj * 128 + n * 16;
;                         sq += quad(row, c, acc[ai][bj][m][n]); }
;                 sq += __shfl_xor(sq, 16); sq += __shfl_xor(sq, 32);
;                 if (fq == 0) ss[(size_t)row * 16 + u.pn * 4 + wc] = sq; }
.LBB0_881:
	s_lshl_b32 s60, s30, 2
	s_ashr_i32 s61, s60, 31
	v_lshl_add_u32 v148, s90, 8, v154
	v_lshl_or_b32 v149, s30, 8, v156
	v_and_b32_e32 v151, 4, v156
	v_mul_u32_u24_e32 v151, 6, v151
	v_lshl_add_u32 v150, v149, 1, v151
	v_lshlrev_b32_e32 v152, 11, v148
	v_add_u32_e32 v152, v152, v150
	v_mov_b32_e32 v153, 0
	v_lshl_add_u64 v[158:159], s[14:15], 0, v[152:153]
	v_lshlrev_b32_e32 v152, 6, v148
	v_lshl_add_u64 v[160:161], s[22:23], 0, v[152:153]
	v_lshl_add_u64 v[160:161], s[60:61], 2, v[160:161]
	s_lshl_b32 s30, s86, 2
	v_lshl_add_u64 v[160:161], v[160:161], 0, s[30:31]
	v_mov_b64_e32 v[152:153], v[158:159]
	global_load_dwordx4 v[164:167], v[158:159], off
	global_load_dwordx4 v[168:171], v[158:159], off offset:256
	s_mov_b64 s[4:5], 0x8000
	v_lshl_add_u64 v[158:159], v[158:159], 0, s[4:5]
	global_load_dwordx4 v[172:175], v[158:159], off
	global_load_dwordx4 v[176:179], v[158:159], off offset:256
	s_mov_b64 s[4:5], 0x8000
	v_lshl_add_u64 v[158:159], v[158:159], 0, s[4:5]
	global_load_dwordx4 v[180:183], v[158:159], off
	global_load_dwordx4 v[184:187], v[158:159], off offset:256
	s_mov_b64 s[4:5], 0x8000
	v_lshl_add_u64 v[158:159], v[158:159], 0, s[4:5]
	global_load_dwordx4 v[204:207], v[158:159], off
	global_load_dwordx4 v[208:211], v[158:159], off offset:256
	s_mov_b64 s[4:5], 0x28000
	v_lshl_add_u64 v[158:159], v[158:159], 0, s[4:5]
	global_load_dwordx4 v[212:215], v[158:159], off
	global_load_dwordx4 v[216:219], v[158:159], off offset:256
	s_mov_b64 s[4:5], 0x8000
	v_lshl_add_u64 v[158:159], v[158:159], 0, s[4:5]
	global_load_dwordx4 v[220:223], v[158:159], off
	global_load_dwordx4 v[224:227], v[158:159], off offset:256
	s_mov_b64 s[4:5], 0x8000
	v_lshl_add_u64 v[158:159], v[158:159], 0, s[4:5]
	global_load_dwordx4 v[228:231], v[158:159], off
	global_load_dwordx4 v[232:235], v[158:159], off offset:256
	s_mov_b64 s[4:5], 0x8000
	v_lshl_add_u64 v[158:159], v[158:159], 0, s[4:5]
	global_load_dwordx4 v[236:239], v[158:159], off
	global_load_dwordx4 v[240:243], v[158:159], off offset:256
	v_permlane16_swap_b32 v126, v122
	v_permlane16_swap_b32 v127, v123
	v_permlane16_swap_b32 v128, v124
	v_permlane16_swap_b32 v129, v125
	v_permlane16_swap_b32 v118, v114
	v_permlane16_swap_b32 v119, v115
	v_permlane16_swap_b32 v120, v116
	v_permlane16_swap_b32 v121, v117
	v_permlane16_swap_b32 v110, v106
	v_permlane16_swap_b32 v111, v107
	v_permlane16_swap_b32 v112, v108
	v_permlane16_swap_b32 v113, v109
	v_permlane16_swap_b32 v102, v98
	v_permlane16_swap_b32 v103, v99
	v_permlane16_swap_b32 v104, v100
	v_permlane16_swap_b32 v105, v101
	v_permlane16_swap_b32 v94, v90
	v_permlane16_swap_b32 v95, v91
	v_permlane16_swap_b32 v96, v92
	v_permlane16_swap_b32 v97, v93
	v_permlane16_swap_b32 v86, v82
	v_permlane16_swap_b32 v87, v83
	v_permlane16_swap_b32 v88, v84
	v_permlane16_swap_b32 v89, v85
	v_permlane16_swap_b32 v78, v74
	v_permlane16_swap_b32 v79, v75
	v_permlane16_swap_b32 v80, v76
	v_permlane16_swap_b32 v81, v77
	v_permlane16_swap_b32 v70, v66
	v_permlane16_swap_b32 v71, v67
	v_permlane16_swap_b32 v72, v68
	v_permlane16_swap_b32 v73, v69
	v_permlane16_swap_b32 v62, v58
	v_permlane16_swap_b32 v63, v59
	v_permlane16_swap_b32 v64, v60
	v_permlane16_swap_b32 v65, v61
	v_permlane16_swap_b32 v54, v50
	v_permlane16_swap_b32 v55, v51
	v_permlane16_swap_b32 v56, v52
	v_permlane16_swap_b32 v57, v53
	v_permlane16_swap_b32 v46, v42
	v_permlane16_swap_b32 v47, v43
	v_permlane16_swap_b32 v48, v44
	v_permlane16_swap_b32 v49, v45
	v_permlane16_swap_b32 v38, v34
	v_permlane16_swap_b32 v39, v35
	v_permlane16_swap_b32 v40, v36
	v_permlane16_swap_b32 v41, v37
	v_permlane16_swap_b32 v30, v26
	v_permlane16_swap_b32 v31, v27
	v_permlane16_swap_b32 v32, v28
	v_permlane16_swap_b32 v33, v29
	v_permlane16_swap_b32 v22, v18
	v_permlane16_swap_b32 v23, v19
	v_permlane16_swap_b32 v24, v20
	v_permlane16_swap_b32 v25, v21
	v_permlane16_swap_b32 v14, v10
	v_permlane16_swap_b32 v15, v11
	v_permlane16_swap_b32 v16, v12
	v_permlane16_swap_b32 v17, v13
	v_permlane16_swap_b32 v6, v2
	v_permlane16_swap_b32 v7, v3
	v_permlane16_swap_b32 v8, v4
	v_permlane16_swap_b32 v9, v5
	s_waitcnt vmcnt(15)
	v_lshlrev_b32_e32 v148, 16, v164
	v_and_b32_e32 v149, 0xffff0000, v164
	v_pk_add_f32 v[126:127], v[126:127], v[148:149]
	v_lshlrev_b32_e32 v150, 16, v165
	v_and_b32_e32 v151, 0xffff0000, v165
	v_pk_add_f32 v[128:129], v[128:129], v[150:151]
	v_lshlrev_b32_e32 v148, 16, v166
	v_and_b32_e32 v149, 0xffff0000, v166
	v_pk_add_f32 v[122:123], v[122:123], v[148:149]
	v_lshlrev_b32_e32 v150, 16, v167
	v_and_b32_e32 v151, 0xffff0000, v167
	v_pk_add_f32 v[124:125], v[124:125], v[150:151]
	v_cvt_pk_bf16_f32 v164, v126, v127
	v_cvt_pk_bf16_f32 v165, v128, v129
	v_cvt_pk_bf16_f32 v166, v122, v123
	v_cvt_pk_bf16_f32 v167, v124, v125
	global_store_dwordx4 v[152:153], v[164:167], off
	v_mul_f32_e32 v127, v127, v127
	v_fmac_f32_e32 v127, v126, v126
	v_mul_f32_e32 v126, v129, v129
	v_fmac_f32_e32 v126, v128, v128
	v_add_f32_e32 v126, v127, v126
	v_mul_f32_e32 v123, v123, v123
	v_fmac_f32_e32 v123, v122, v122
	v_mul_f32_e32 v122, v125, v125
	v_fmac_f32_e32 v122, v124, v124
	v_add_f32_e32 v122, v123, v122
	v_add_f32_e32 v126, v126, v122
	s_waitcnt vmcnt(15)
; __device__ __forceinline__ float bflo(unsigned w) { return __uint_as_float(w << 16); }
; __device__ __forceinline__ float bfhi(unsigned w) { return __uint_as_float(w & 0xffff0000u); }
; __device__ __forceinline__ unsigned pk2(float lo, float hi) { f32x2 v = {lo, hi}; bf16x2_t b = __builtin_convertvector(v, bf16x2_t); return __builtin_bit_cast(unsigned, b); }
;     template <int QPR> __device__ __forceinline__ void tailq(int row, int c, const f32x4 v, int) const { quad(row, c, v); }
;     template <int QPR> __device__ __forceinline__ void tailq(int row, int c, const f32x4 v, int) const { quad(row, c, v); }
;     __device__ __forceinline__ float quad(int row, int c, const f32x4 a) const {
;         bf16_t* xp = XB + (size_t)row * D + c;
;         const u32x2 xw = *(const u32x2*)xp;
;         const f32x4 x = (f32x4){bflo(xw.x), bfhi(xw.x), bflo(xw.y), bfhi(xw.y)} + a;
;         u32x2 w; w.x = pk2(x[0], x[1]); w.y = pk2(x[2], x[3]);
;         *(u32x2*)xp = w;
;         return (x[0] * x[0] + x[1] * x[1]) + (x[2] * x[2] + x[3] * x[3]); }
;     template <int QPR> __device__ __forceinline__ void tailq(int row, int c, const f32x4 v, int c0) const {
;         float sq = quad(row, c, v);
; #pragma unroll
;         for (int o = 1; o < QPR; o <<= 1) sq += __shfl_xor(sq, o);
;         if ((threadIdx.x & (QPR - 1)) == 0) ss[(size_t)row * 16 + (c0 >> 6)] = sq; }
;     __device__ __forceinline__ void operator()(const f32x4 (&acc)[2][2][4][2], const pg8::Unit& u, int wr, int wc, int fr, int fq) const {
;         const int row0 = u.pm * 256 + wr * 64 + fr, col0 = u.pn * 256 + wc * 32 + 4 * fq;
; #pragma unroll
;         for (int ai = 0; ai < 2; ++ai)
; #pragma unroll
;             for (int m = 0; m < 4; ++m) { const int row = row0 + ai * 128 + m * 16; float sq = 0.f;
; #pragma unroll
;                 for (int bj = 0; bj < 2; ++bj)
; #pragma unroll
;                     for (int n = 0; n < 2; ++n) { const int c = col0 + bj * 128 + n * 16;
;                         sq += quad(row, c, acc[ai][bj][m][n]); }
;                 sq += __shfl_xor(sq, 16); sq += __shfl_xor(sq, 32);
;                 if (fq == 0) ss[(size_t)row * 16 + u.pn * 4 + wc] = sq; }
	v_lshlrev_b32_e32 v148, 16, v168
	v_and_b32_e32 v149, 0xffff0000, v168
	v_pk_add_f32 v[118:119], v[118:119], v[148:149]
	v_lshlrev_b32_e32 v150, 16, v169
	v_and_b32_e32 v151, 0xffff0000, v169
	v_pk_add_f32 v[120:121], v[120:121], v[150:151]
	v_lshlrev_b32_e32 v148, 16, v170
	v_and_b32_e32 v149, 0xffff0000, v170
	v_pk_add_f32 v[114:115], v[114:115], v[148:149]
	v_lshlrev_b32_e32 v150, 16, v171
	v_and_b32_e32 v151, 0xffff0000, v171
	v_pk_add_f32 v[116:117], v[116:117], v[150:151]
	v_cvt_pk_bf16_f32 v168, v118, v119
	v_cvt_pk_bf16_f32 v169, v120, v121
	v_cvt_pk_bf16_f32 v170, v114, v115
	v_cvt_pk_bf16_f32 v171, v116, v117
	global_store_dwordx4 v[152:153], v[168:171], off offset:256
	s_mov_b64 s[4:5], 0x8000
	v_lshl_add_u64 v[152:153], v[152:153], 0, s[4:5]
	v_mul_f32_e32 v119, v119, v119
	v_fmac_f32_e32 v119, v118, v118
	v_mul_f32_e32 v118, v121, v121
	v_fmac_f32_e32 v118, v120, v120
	v_add_f32_e32 v118, v119, v118
	v_mul_f32_e32 v115, v115, v115
	v_fmac_f32_e32 v115, v114, v114
	v_mul_f32_e32 v114, v117, v117
	v_fmac_f32_e32 v114, v116, v116
	v_add_f32_e32 v114, v115, v114
	v_add_f32_e32 v126, v126, v118
	v_add_f32_e32 v126, v126, v114
	v_mov_b32_e32 v118, v126
	v_mov_b32_e32 v119, v126
	s_nop 1
	v_permlane16_swap_b32 v118, v119
	v_add_f32_e32 v126, v126, v119
	v_mov_b32_e32 v118, v126
	v_mov_b32_e32 v119, v126
	s_nop 1
	v_permlane32_swap_b32 v118, v119
	v_add_f32_e32 v126, v126, v119
	s_waitcnt vmcnt(15)
	v_lshlrev_b32_e32 v148, 16, v172
	v_and_b32_e32 v149, 0xffff0000, v172
	v_pk_add_f32 v[110:111], v[110:111], v[148:149]
	v_lshlrev_b32_e32 v150, 16, v173
	v_and_b32_e32 v151, 0xffff0000, v173
	v_pk_add_f32 v[112:113], v[112:113], v[150:151]
	v_lshlrev_b32_e32 v148, 16, v174
	v_and_b32_e32 v149, 0xffff0000, v174
	v_pk_add_f32 v[106:107], v[106:107], v[148:149]
	v_lshlrev_b32_e32 v150, 16, v175
	v_and_b32_e32 v151, 0xffff0000, v175
	v_pk_add_f32 v[108:109], v[108:109], v[150:151]
	v_cvt_pk_bf16_f32 v172, v110, v111
	v_cvt_pk_bf16_f32 v173, v112, v113
	v_cvt_pk_bf16_f32 v174, v106, v107
	v_cvt_pk_bf16_f32 v175, v108, v109
	global_store_dwordx4 v[152:153], v[172:175], off
	v_mul_f32_e32 v111, v111, v111
	v_fmac_f32_e32 v111, v110, v110
	v_mul_f32_e32 v110, v113, v113
	v_fmac_f32_e32 v110, v112, v112
	v_add_f32_e32 v110, v111, v110
	v_mul_f32_e32 v107, v107, v107
	v_fmac_f32_e32 v107, v106, v106
	v_mul_f32_e32 v106, v109, v109
	v_fmac_f32_e32 v106, v108, v108
	v_add_f32_e32 v106, v107, v106
	v_add_f32_e32 v110, v110, v106
	s_waitcnt vmcnt(15)
	v_lshlrev_b32_e32 v148, 16, v176
	v_and_b32_e32 v149, 0xffff0000, v176
	v_pk_add_f32 v[102:103], v[102:103], v[148:149]
	v_lshlrev_b32_e32 v150, 16, v177
	v_and_b32_e32 v151, 0xffff0000, v177
	v_pk_add_f32 v[104:105], v[104:105], v[150:151]
	v_lshlrev_b32_e32 v148, 16, v178
	v_and_b32_e32 v149, 0xffff0000, v178
	v_pk_add_f32 v[98:99], v[98:99], v[148:149]
	v_lshlrev_b32_e32 v150, 16, v179
	v_and_b32_e32 v151, 0xffff0000, v179
	v_pk_add_f32 v[100:101], v[100:101], v[150:151]
	v_cvt_pk_bf16_f32 v176, v102, v103
	v_cvt_pk_bf16_f32 v177, v104, v105
	v_cvt_pk_bf16_f32 v178, v98, v99
	v_cvt_pk_bf16_f32 v179, v100, v101
	global_store_dwordx4 v[152:153], v[176:179], off offset:256
	s_mov_b64 s[4:5], 0x8000
	v_lshl_add_u64 v[152:153], v[152:153], 0, s[4:5]
	v_mul_f32_e32 v103, v103, v103
	v_fmac_f32_e32 v103, v102, v102
	v_mul_f32_e32 v102, v105, v105
	v_fmac_f32_e32 v102, v104, v104
	v_add_f32_e32 v102, v103, v102
	v_mul_f32_e32 v99, v99, v99
	v_fmac_f32_e32 v99, v98, v98
	v_mul_f32_e32 v98, v101, v101
	v_fmac_f32_e32 v98, v100, v100
	v_add_f32_e32 v98, v99, v98
	v_add_f32_e32 v110, v110, v102
	v_add_f32_e32 v110, v110, v98
	v_mov_b32_e32 v102, v110
	v_mov_b32_e32 v103, v110
	s_nop 1
	v_permlane16_swap_b32 v102, v103
	v_add_f32_e32 v110, v110, v103
	v_mov_b32_e32 v102, v110
	v_mov_b32_e32 v103, v110
	s_nop 1
	v_permlane32_swap_b32 v102, v103
	v_add_f32_e32 v110, v110, v103
	s_waitcnt vmcnt(15)
	v_lshlrev_b32_e32 v148, 16, v180
	v_and_b32_e32 v149, 0xffff0000, v180
	v_pk_add_f32 v[94:95], v[94:95], v[148:149]
	v_lshlrev_b32_e32 v150, 16, v181
	v_and_b32_e32 v151, 0xffff0000, v181
	v_pk_add_f32 v[96:97], v[96:97], v[150:151]
	v_lshlrev_b32_e32 v148, 16, v182
	v_and_b32_e32 v149, 0xffff0000, v182
	v_pk_add_f32 v[90:91], v[90:91], v[148:149]
	v_lshlrev_b32_e32 v150, 16, v183
	v_and_b32_e32 v151, 0xffff0000, v183
	v_pk_add_f32 v[92:93], v[92:93], v[150:151]
	v_cvt_pk_bf16_f32 v180, v94, v95
	v_cvt_pk_bf16_f32 v181, v96, v97
	v_cvt_pk_bf16_f32 v182, v90, v91
	v_cvt_pk_bf16_f32 v183, v92, v93
	global_store_dwordx4 v[152:153], v[180:183], off
	v_mul_f32_e32 v95, v95, v95
	v_fmac_f32_e32 v95, v94, v94
	v_mul_f32_e32 v94, v97, v97
	v_fmac_f32_e32 v94, v96, v96
	v_add_f32_e32 v94, v95, v94
	v_mul_f32_e32 v91, v91, v91
	v_fmac_f32_e32 v91, v90, v90
	v_mul_f32_e32 v90, v93, v93
	v_fmac_f32_e32 v90, v92, v92
	v_add_f32_e32 v90, v91, v90
	v_add_f32_e32 v94, v94, v90
	s_waitcnt vmcnt(15)
	v_lshlrev_b32_e32 v148, 16, v184
	v_and_b32_e32 v149, 0xffff0000, v184
	v_pk_add_f32 v[86:87], v[86:87], v[148:149]
	v_lshlrev_b32_e32 v150, 16, v185
	v_and_b32_e32 v151, 0xffff0000, v185
	v_pk_add_f32 v[88:89], v[88:89], v[150:151]
	v_lshlrev_b32_e32 v148, 16, v186
	v_and_b32_e32 v149, 0xffff0000, v186
	v_pk_add_f32 v[82:83], v[82:83], v[148:149]
	v_lshlrev_b32_e32 v150, 16, v187
	v_and_b32_e32 v151, 0xffff0000, v187
	v_pk_add_f32 v[84:85], v[84:85], v[150:151]
	v_cvt_pk_bf16_f32 v184, v86, v87
	v_cvt_pk_bf16_f32 v185, v88, v89
	v_cvt_pk_bf16_f32 v186, v82, v83
	v_cvt_pk_bf16_f32 v187, v84, v85
	global_store_dwordx4 v[152:153], v[184:187], off offset:256
	s_mov_b64 s[4:5], 0x8000
	v_lshl_add_u64 v[152:153], v[152:153], 0, s[4:5]
	v_mul_f32_e32 v87, v87, v87
	v_fmac_f32_e32 v87, v86, v86
	v_mul_f32_e32 v86, v89, v89
	v_fmac_f32_e32 v86, v88, v88
	v_add_f32_e32 v86, v87, v86
	v_mul_f32_e32 v83, v83, v83
	v_fmac_f32_e32 v83, v82, v82
	v_mul_f32_e32 v82, v85, v85
	v_fmac_f32_e32 v82, v84, v84
	v_add_f32_e32 v82, v83, v82
	v_add_f32_e32 v94, v94, v86
	v_add_f32_e32 v94, v94, v82
	v_mov_b32_e32 v86, v94
	v_mov_b32_e32 v87, v94
	s_nop 1
	v_permlane16_swap_b32 v86, v87
	v_add_f32_e32 v94, v94, v87
	v_mov_b32_e32 v86, v94
	v_mov_b32_e32 v87, v94
	s_nop 1
	v_permlane32_swap_b32 v86, v87
	v_add_f32_e32 v94, v94, v87
	s_waitcnt vmcnt(15)
; __device__ __forceinline__ float bflo(unsigned w) { return __uint_as_float(w << 16); }
; __device__ __forceinline__ float bfhi(unsigned w) { return __uint_as_float(w & 0xffff0000u); }
; __device__ __forceinline__ unsigned pk2(float lo, float hi) { f32x2 v = {lo, hi}; bf16x2_t b = __builtin_convertvector(v, bf16x2_t); return __builtin_bit_cast(unsigned, b); }
;     template <int QPR> __device__ __forceinline__ void tailq(int row, int c, const f32x4 v, int) const { quad(row, c, v); }
;     template <int QPR> __device__ __forceinline__ void tailq(int row, int c, const f32x4 v, int) const { quad(row, c, v); }
;     __device__ __forceinline__ float quad(int row, int c, const f32x4 a) const {
;         bf16_t* xp = XB + (size_t)row * D + c;
;         const u32x2 xw = *(const u32x2*)xp;
;         const f32x4 x = (f32x4){bflo(xw.x), bfhi(xw.x), bflo(xw.y), bfhi(xw.y)} + a;
;         u32x2 w; w.x = pk2(x[0], x[1]); w.y = pk2(x[2], x[3]);
;         *(u32x2*)xp = w;
;         return (x[0] * x[0] + x[1] * x[1]) + (x[2] * x[2] + x[3] * x[3]); }
;     template <int QPR> __device__ __forceinline__ void tailq(int row, int c, const f32x4 v, int c0) const {
;         float sq = quad(row, c, v);
; #pragma unroll
;         for (int o = 1; o < QPR; o <<= 1) sq += __shfl_xor(sq, o);
;         if ((threadIdx.x & (QPR - 1)) == 0) ss[(size_t)row * 16 + (c0 >> 6)] = sq; }
;     __device__ __forceinline__ void operator()(const f32x4 (&acc)[2][2][4][2], const pg8::Unit& u, int wr, int wc, int fr, int fq) const {
;         const int row0 = u.pm * 256 + wr * 64 + fr, col0 = u.pn * 256 + wc * 32 + 4 * fq;
; #pragma unroll
;         for (int ai = 0; ai < 2; ++ai)
; #pragma unroll
;             for (int m = 0; m < 4; ++m) { const int row = row0 + ai * 128 + m * 16; float sq = 0.f;
; #pragma unroll
;                 for (int bj = 0; bj < 2; ++bj)
; #pragma unroll
;                     for (int n = 0; n < 2; ++n) { const int c = col0 + bj * 128 + n * 16;
;                         sq += quad(row, c, acc[ai][bj][m][n]); }
;                 sq += __shfl_xor(sq, 16); sq += __shfl_xor(sq, 32);
;                 if (fq == 0) ss[(size_t)row * 16 + u.pn * 4 + wc] = sq; }
	v_lshlrev_b32_e32 v148, 16, v204
	v_and_b32_e32 v149, 0xffff0000, v204
	v_pk_add_f32 v[78:79], v[78:79], v[148:149]
	v_lshlrev_b32_e32 v150, 16, v205
	v_and_b32_e32 v151, 0xffff0000, v205
	v_pk_add_f32 v[80:81], v[80:81], v[150:151]
	v_lshlrev_b32_e32 v148, 16, v206
	v_and_b32_e32 v149, 0xffff0000, v206
	v_pk_add_f32 v[74:75], v[74:75], v[148:149]
	v_lshlrev_b32_e32 v150, 16, v207
	v_and_b32_e32 v151, 0xffff0000, v207
	v_pk_add_f32 v[76:77], v[76:77], v[150:151]
	v_cvt_pk_bf16_f32 v204, v78, v79
	v_cvt_pk_bf16_f32 v205, v80, v81
	v_cvt_pk_bf16_f32 v206, v74, v75
	v_cvt_pk_bf16_f32 v207, v76, v77
	global_store_dwordx4 v[152:153], v[204:207], off
	v_mul_f32_e32 v79, v79, v79
	v_fmac_f32_e32 v79, v78, v78
	v_mul_f32_e32 v78, v81, v81
	v_fmac_f32_e32 v78, v80, v80
	v_add_f32_e32 v78, v79, v78
	v_mul_f32_e32 v75, v75, v75
	v_fmac_f32_e32 v75, v74, v74
	v_mul_f32_e32 v74, v77, v77
	v_fmac_f32_e32 v74, v76, v76
	v_add_f32_e32 v74, v75, v74
	v_add_f32_e32 v78, v78, v74
	s_waitcnt vmcnt(15)
	v_lshlrev_b32_e32 v148, 16, v208
	v_and_b32_e32 v149, 0xffff0000, v208
	v_pk_add_f32 v[70:71], v[70:71], v[148:149]
	v_lshlrev_b32_e32 v150, 16, v209
	v_and_b32_e32 v151, 0xffff0000, v209
	v_pk_add_f32 v[72:73], v[72:73], v[150:151]
	v_lshlrev_b32_e32 v148, 16, v210
	v_and_b32_e32 v149, 0xffff0000, v210
	v_pk_add_f32 v[66:67], v[66:67], v[148:149]
	v_lshlrev_b32_e32 v150, 16, v211
	v_and_b32_e32 v151, 0xffff0000, v211
	v_pk_add_f32 v[68:69], v[68:69], v[150:151]
	v_cvt_pk_bf16_f32 v208, v70, v71
	v_cvt_pk_bf16_f32 v209, v72, v73
	v_cvt_pk_bf16_f32 v210, v66, v67
	v_cvt_pk_bf16_f32 v211, v68, v69
	global_store_dwordx4 v[152:153], v[208:211], off offset:256
	s_mov_b64 s[4:5], 0x28000
	v_lshl_add_u64 v[152:153], v[152:153], 0, s[4:5]
	v_mul_f32_e32 v71, v71, v71
	v_fmac_f32_e32 v71, v70, v70
	v_mul_f32_e32 v70, v73, v73
	v_fmac_f32_e32 v70, v72, v72
	v_add_f32_e32 v70, v71, v70
	v_mul_f32_e32 v67, v67, v67
	v_fmac_f32_e32 v67, v66, v66
	v_mul_f32_e32 v66, v69, v69
	v_fmac_f32_e32 v66, v68, v68
	v_add_f32_e32 v66, v67, v66
	v_add_f32_e32 v78, v78, v70
	v_add_f32_e32 v78, v78, v66
	v_mov_b32_e32 v70, v78
	v_mov_b32_e32 v71, v78
	s_nop 1
	v_permlane16_swap_b32 v70, v71
	v_add_f32_e32 v78, v78, v71
	v_mov_b32_e32 v70, v78
	v_mov_b32_e32 v71, v78
	s_nop 1
	v_permlane32_swap_b32 v70, v71
	v_add_f32_e32 v78, v78, v71
	s_waitcnt vmcnt(15)
	v_lshlrev_b32_e32 v148, 16, v212
	v_and_b32_e32 v149, 0xffff0000, v212
	v_pk_add_f32 v[62:63], v[62:63], v[148:149]
	v_lshlrev_b32_e32 v150, 16, v213
	v_and_b32_e32 v151, 0xffff0000, v213
	v_pk_add_f32 v[64:65], v[64:65], v[150:151]
	v_lshlrev_b32_e32 v148, 16, v214
	v_and_b32_e32 v149, 0xffff0000, v214
	v_pk_add_f32 v[58:59], v[58:59], v[148:149]
	v_lshlrev_b32_e32 v150, 16, v215
	v_and_b32_e32 v151, 0xffff0000, v215
	v_pk_add_f32 v[60:61], v[60:61], v[150:151]
	v_cvt_pk_bf16_f32 v212, v62, v63
	v_cvt_pk_bf16_f32 v213, v64, v65
	v_cvt_pk_bf16_f32 v214, v58, v59
	v_cvt_pk_bf16_f32 v215, v60, v61
	global_store_dwordx4 v[152:153], v[212:215], off
	v_mul_f32_e32 v63, v63, v63
	v_fmac_f32_e32 v63, v62, v62
	v_mul_f32_e32 v62, v65, v65
	v_fmac_f32_e32 v62, v64, v64
	v_add_f32_e32 v62, v63, v62
	v_mul_f32_e32 v59, v59, v59
	v_fmac_f32_e32 v59, v58, v58
	v_mul_f32_e32 v58, v61, v61
	v_fmac_f32_e32 v58, v60, v60
	v_add_f32_e32 v58, v59, v58
	v_add_f32_e32 v62, v62, v58
	s_waitcnt vmcnt(15)
	v_lshlrev_b32_e32 v148, 16, v216
	v_and_b32_e32 v149, 0xffff0000, v216
	v_pk_add_f32 v[54:55], v[54:55], v[148:149]
	v_lshlrev_b32_e32 v150, 16, v217
	v_and_b32_e32 v151, 0xffff0000, v217
	v_pk_add_f32 v[56:57], v[56:57], v[150:151]
	v_lshlrev_b32_e32 v148, 16, v218
	v_and_b32_e32 v149, 0xffff0000, v218
	v_pk_add_f32 v[50:51], v[50:51], v[148:149]
	v_lshlrev_b32_e32 v150, 16, v219
	v_and_b32_e32 v151, 0xffff0000, v219
	v_pk_add_f32 v[52:53], v[52:53], v[150:151]
	v_cvt_pk_bf16_f32 v216, v54, v55
	v_cvt_pk_bf16_f32 v217, v56, v57
	v_cvt_pk_bf16_f32 v218, v50, v51
	v_cvt_pk_bf16_f32 v219, v52, v53
	global_store_dwordx4 v[152:153], v[216:219], off offset:256
	s_mov_b64 s[4:5], 0x8000
	v_lshl_add_u64 v[152:153], v[152:153], 0, s[4:5]
	v_mul_f32_e32 v55, v55, v55
	v_fmac_f32_e32 v55, v54, v54
	v_mul_f32_e32 v54, v57, v57
	v_fmac_f32_e32 v54, v56, v56
	v_add_f32_e32 v54, v55, v54
	v_mul_f32_e32 v51, v51, v51
	v_fmac_f32_e32 v51, v50, v50
	v_mul_f32_e32 v50, v53, v53
	v_fmac_f32_e32 v50, v52, v52
	v_add_f32_e32 v50, v51, v50
	v_add_f32_e32 v62, v62, v54
	v_add_f32_e32 v62, v62, v50
	v_mov_b32_e32 v54, v62
	v_mov_b32_e32 v55, v62
	s_nop 1
	v_permlane16_swap_b32 v54, v55
	v_add_f32_e32 v62, v62, v55
	v_mov_b32_e32 v54, v62
	v_mov_b32_e32 v55, v62
	s_nop 1
	v_permlane32_swap_b32 v54, v55
	v_add_f32_e32 v62, v62, v55
	s_waitcnt vmcnt(15)
	v_lshlrev_b32_e32 v148, 16, v220
	v_and_b32_e32 v149, 0xffff0000, v220
	v_pk_add_f32 v[46:47], v[46:47], v[148:149]
	v_lshlrev_b32_e32 v150, 16, v221
	v_and_b32_e32 v151, 0xffff0000, v221
	v_pk_add_f32 v[48:49], v[48:49], v[150:151]
	v_lshlrev_b32_e32 v148, 16, v222
	v_and_b32_e32 v149, 0xffff0000, v222
	v_pk_add_f32 v[42:43], v[42:43], v[148:149]
	v_lshlrev_b32_e32 v150, 16, v223
	v_and_b32_e32 v151, 0xffff0000, v223
	v_pk_add_f32 v[44:45], v[44:45], v[150:151]
	v_cvt_pk_bf16_f32 v220, v46, v47
	v_cvt_pk_bf16_f32 v221, v48, v49
	v_cvt_pk_bf16_f32 v222, v42, v43
	v_cvt_pk_bf16_f32 v223, v44, v45
	global_store_dwordx4 v[152:153], v[220:223], off
	v_mul_f32_e32 v47, v47, v47
	v_fmac_f32_e32 v47, v46, v46
	v_mul_f32_e32 v46, v49, v49
	v_fmac_f32_e32 v46, v48, v48
	v_add_f32_e32 v46, v47, v46
	v_mul_f32_e32 v43, v43, v43
	v_fmac_f32_e32 v43, v42, v42
	v_mul_f32_e32 v42, v45, v45
	v_fmac_f32_e32 v42, v44, v44
	v_add_f32_e32 v42, v43, v42
	v_add_f32_e32 v46, v46, v42
	s_waitcnt vmcnt(15)
; __device__ __forceinline__ float bflo(unsigned w) { return __uint_as_float(w << 16); }
; __device__ __forceinline__ float bfhi(unsigned w) { return __uint_as_float(w & 0xffff0000u); }
; __device__ __forceinline__ unsigned pk2(float lo, float hi) { f32x2 v = {lo, hi}; bf16x2_t b = __builtin_convertvector(v, bf16x2_t); return __builtin_bit_cast(unsigned, b); }
;     template <int QPR> __device__ __forceinline__ void tailq(int row, int c, const f32x4 v, int) const { quad(row, c, v); }
;     template <int QPR> __device__ __forceinline__ void tailq(int row, int c, const f32x4 v, int) const { quad(row, c, v); }
;     __device__ __forceinline__ float quad(int row, int c, const f32x4 a) const {
;         bf16_t* xp = XB + (size_t)row * D + c;
;         const u32x2 xw = *(const u32x2*)xp;
;         const f32x4 x = (f32x4){bflo(xw.x), bfhi(xw.x), bflo(xw.y), bfhi(xw.y)} + a;
;         u32x2 w; w.x = pk2(x[0], x[1]); w.y = pk2(x[2], x[3]);
;         *(u32x2*)xp = w;
;         return (x[0] * x[0] + x[1] * x[1]) + (x[2] * x[2] + x[3] * x[3]); }
;     template <int QPR> __device__ __forceinline__ void tailq(int row, int c, const f32x4 v, int c0) const {
;         float sq = quad(row, c, v);
; #pragma unroll
;         for (int o = 1; o < QPR; o <<= 1) sq += __shfl_xor(sq, o);
;         if ((threadIdx.x & (QPR - 1)) == 0) ss[(size_t)row * 16 + (c0 >> 6)] = sq; }
;     __device__ __forceinline__ void operator()(const f32x4 (&acc)[2][2][4][2], const pg8::Unit& u, int wr, int wc, int fr, int fq) const {
;         const int row0 = u.pm * 256 + wr * 64 + fr, col0 = u.pn * 256 + wc * 32 + 4 * fq;
; #pragma unroll
;         for (int ai = 0; ai < 2; ++ai)
; #pragma unroll
;             for (int m = 0; m < 4; ++m) { const int row = row0 + ai * 128 + m * 16; float sq = 0.f;
; #pragma unroll
;                 for (int bj = 0; bj < 2; ++bj)
; #pragma unroll
;                     for (int n = 0; n < 2; ++n) { const int c = col0 + bj * 128 + n * 16;
;                         sq += quad(row, c, acc[ai][bj][m][n]); }
;                 sq += __shfl_xor(sq, 16); sq += __shfl_xor(sq, 32);
;                 if (fq == 0) ss[(size_t)row * 16 + u.pn * 4 + wc] = sq; }
	v_lshlrev_b32_e32 v148, 16, v224
	v_and_b32_e32 v149, 0xffff0000, v224
	v_pk_add_f32 v[38:39], v[38:39], v[148:149]
	v_lshlrev_b32_e32 v150, 16, v225
	v_and_b32_e32 v151, 0xffff0000, v225
	v_pk_add_f32 v[40:41], v[40:41], v[150:151]
	v_lshlrev_b32_e32 v148, 16, v226
	v_and_b32_e32 v149, 0xffff0000, v226
	v_pk_add_f32 v[34:35], v[34:35], v[148:149]
	v_lshlrev_b32_e32 v150, 16, v227
	v_and_b32_e32 v151, 0xffff0000, v227
	v_pk_add_f32 v[36:37], v[36:37], v[150:151]
	v_cvt_pk_bf16_f32 v224, v38, v39
	v_cvt_pk_bf16_f32 v225, v40, v41
	v_cvt_pk_bf16_f32 v226, v34, v35
	v_cvt_pk_bf16_f32 v227, v36, v37
	global_store_dwordx4 v[152:153], v[224:227], off offset:256
	s_mov_b64 s[4:5], 0x8000
	v_lshl_add_u64 v[152:153], v[152:153], 0, s[4:5]
	v_mul_f32_e32 v39, v39, v39
	v_fmac_f32_e32 v39, v38, v38
	v_mul_f32_e32 v38, v41, v41
	v_fmac_f32_e32 v38, v40, v40
	v_add_f32_e32 v38, v39, v38
	v_mul_f32_e32 v35, v35, v35
	v_fmac_f32_e32 v35, v34, v34
	v_mul_f32_e32 v34, v37, v37
	v_fmac_f32_e32 v34, v36, v36
	v_add_f32_e32 v34, v35, v34
	v_add_f32_e32 v46, v46, v38
	v_add_f32_e32 v46, v46, v34
	v_mov_b32_e32 v38, v46
	v_mov_b32_e32 v39, v46
	s_nop 1
	v_permlane16_swap_b32 v38, v39
	v_add_f32_e32 v46, v46, v39
	v_mov_b32_e32 v38, v46
	v_mov_b32_e32 v39, v46
	s_nop 1
	v_permlane32_swap_b32 v38, v39
	v_add_f32_e32 v46, v46, v39
	s_waitcnt vmcnt(15)
	v_lshlrev_b32_e32 v148, 16, v228
	v_and_b32_e32 v149, 0xffff0000, v228
	v_pk_add_f32 v[30:31], v[30:31], v[148:149]
	v_lshlrev_b32_e32 v150, 16, v229
	v_and_b32_e32 v151, 0xffff0000, v229
	v_pk_add_f32 v[32:33], v[32:33], v[150:151]
	v_lshlrev_b32_e32 v148, 16, v230
	v_and_b32_e32 v149, 0xffff0000, v230
	v_pk_add_f32 v[26:27], v[26:27], v[148:149]
	v_lshlrev_b32_e32 v150, 16, v231
	v_and_b32_e32 v151, 0xffff0000, v231
	v_pk_add_f32 v[28:29], v[28:29], v[150:151]
	v_cvt_pk_bf16_f32 v228, v30, v31
	v_cvt_pk_bf16_f32 v229, v32, v33
	v_cvt_pk_bf16_f32 v230, v26, v27
	v_cvt_pk_bf16_f32 v231, v28, v29
	global_store_dwordx4 v[152:153], v[228:231], off
	v_mul_f32_e32 v31, v31, v31
	v_fmac_f32_e32 v31, v30, v30
	v_mul_f32_e32 v30, v33, v33
	v_fmac_f32_e32 v30, v32, v32
	v_add_f32_e32 v30, v31, v30
	v_mul_f32_e32 v27, v27, v27
	v_fmac_f32_e32 v27, v26, v26
	v_mul_f32_e32 v26, v29, v29
	v_fmac_f32_e32 v26, v28, v28
	v_add_f32_e32 v26, v27, v26
	v_add_f32_e32 v30, v30, v26
	s_waitcnt vmcnt(15)
	v_lshlrev_b32_e32 v148, 16, v232
	v_and_b32_e32 v149, 0xffff0000, v232
	v_pk_add_f32 v[22:23], v[22:23], v[148:149]
	v_lshlrev_b32_e32 v150, 16, v233
	v_and_b32_e32 v151, 0xffff0000, v233
	v_pk_add_f32 v[24:25], v[24:25], v[150:151]
	v_lshlrev_b32_e32 v148, 16, v234
	v_and_b32_e32 v149, 0xffff0000, v234
	v_pk_add_f32 v[18:19], v[18:19], v[148:149]
	v_lshlrev_b32_e32 v150, 16, v235
	v_and_b32_e32 v151, 0xffff0000, v235
	v_pk_add_f32 v[20:21], v[20:21], v[150:151]
	v_cvt_pk_bf16_f32 v232, v22, v23
	v_cvt_pk_bf16_f32 v233, v24, v25
	v_cvt_pk_bf16_f32 v234, v18, v19
	v_cvt_pk_bf16_f32 v235, v20, v21
	global_store_dwordx4 v[152:153], v[232:235], off offset:256
	s_mov_b64 s[4:5], 0x8000
	v_lshl_add_u64 v[152:153], v[152:153], 0, s[4:5]
	v_mul_f32_e32 v23, v23, v23
	v_fmac_f32_e32 v23, v22, v22
	v_mul_f32_e32 v22, v25, v25
	v_fmac_f32_e32 v22, v24, v24
	v_add_f32_e32 v22, v23, v22
	v_mul_f32_e32 v19, v19, v19
	v_fmac_f32_e32 v19, v18, v18
	v_mul_f32_e32 v18, v21, v21
	v_fmac_f32_e32 v18, v20, v20
	v_add_f32_e32 v18, v19, v18
	v_add_f32_e32 v30, v30, v22
	v_add_f32_e32 v30, v30, v18
	v_mov_b32_e32 v22, v30
	v_mov_b32_e32 v23, v30
	s_nop 1
	v_permlane16_swap_b32 v22, v23
	v_add_f32_e32 v30, v30, v23
	v_mov_b32_e32 v22, v30
	v_mov_b32_e32 v23, v30
	s_nop 1
	v_permlane32_swap_b32 v22, v23
	v_add_f32_e32 v30, v30, v23
	s_waitcnt vmcnt(15)
	v_lshlrev_b32_e32 v148, 16, v236
	v_and_b32_e32 v149, 0xffff0000, v236
	v_pk_add_f32 v[14:15], v[14:15], v[148:149]
	v_lshlrev_b32_e32 v150, 16, v237
	v_and_b32_e32 v151, 0xffff0000, v237
	v_pk_add_f32 v[16:17], v[16:17], v[150:151]
	v_lshlrev_b32_e32 v148, 16, v238
	v_and_b32_e32 v149, 0xffff0000, v238
	v_pk_add_f32 v[10:11], v[10:11], v[148:149]
	v_lshlrev_b32_e32 v150, 16, v239
	v_and_b32_e32 v151, 0xffff0000, v239
	v_pk_add_f32 v[12:13], v[12:13], v[150:151]
	v_cvt_pk_bf16_f32 v236, v14, v15
	v_cvt_pk_bf16_f32 v237, v16, v17
	v_cvt_pk_bf16_f32 v238, v10, v11
	v_cvt_pk_bf16_f32 v239, v12, v13
	global_store_dwordx4 v[152:153], v[236:239], off
	v_mul_f32_e32 v15, v15, v15
	v_fmac_f32_e32 v15, v14, v14
	v_mul_f32_e32 v14, v17, v17
	v_fmac_f32_e32 v14, v16, v16
	v_add_f32_e32 v14, v15, v14
	v_mul_f32_e32 v11, v11, v11
	v_fmac_f32_e32 v11, v10, v10
	v_mul_f32_e32 v10, v13, v13
	v_fmac_f32_e32 v10, v12, v12
	v_add_f32_e32 v10, v11, v10
	v_add_f32_e32 v14, v14, v10
	s_waitcnt vmcnt(15)
	v_lshlrev_b32_e32 v148, 16, v240
	v_and_b32_e32 v149, 0xffff0000, v240
	v_pk_add_f32 v[6:7], v[6:7], v[148:149]
	v_lshlrev_b32_e32 v150, 16, v241
	v_and_b32_e32 v151, 0xffff0000, v241
	v_pk_add_f32 v[8:9], v[8:9], v[150:151]
	v_lshlrev_b32_e32 v148, 16, v242
	v_and_b32_e32 v149, 0xffff0000, v242
	v_pk_add_f32 v[2:3], v[2:3], v[148:149]
	v_lshlrev_b32_e32 v150, 16, v243
	v_and_b32_e32 v151, 0xffff0000, v243
	v_pk_add_f32 v[4:5], v[4:5], v[150:151]
	v_cvt_pk_bf16_f32 v240, v6, v7
	v_cvt_pk_bf16_f32 v241, v8, v9
	v_cvt_pk_bf16_f32 v242, v2, v3
	v_cvt_pk_bf16_f32 v243, v4, v5
	global_store_dwordx4 v[152:153], v[240:243], off offset:256
	v_mul_f32_e32 v7, v7, v7
	v_fmac_f32_e32 v7, v6, v6
	v_mul_f32_e32 v6, v9, v9
	v_fmac_f32_e32 v6, v8, v8
	v_add_f32_e32 v6, v7, v6
	v_mul_f32_e32 v3, v3, v3
	v_fmac_f32_e32 v3, v2, v2
	v_mul_f32_e32 v2, v5, v5
	v_fmac_f32_e32 v2, v4, v4
	v_add_f32_e32 v2, v3, v2
	v_add_f32_e32 v14, v14, v6
	v_add_f32_e32 v14, v14, v2
	v_mov_b32_e32 v6, v14
	v_mov_b32_e32 v7, v14
	s_nop 1
	v_permlane16_swap_b32 v6, v7
	v_add_f32_e32 v14, v14, v7
	v_mov_b32_e32 v6, v14
	v_mov_b32_e32 v7, v14
	s_nop 1
	v_permlane32_swap_b32 v6, v7
	v_add_f32_e32 v14, v14, v7
	s_mov_b64 s[4:5], 0x2000
	v_lshl_add_u64 v[148:149], v[160:161], 0, s[4:5]
	s_and_saveexec_b64 s[4:5], s[38:39]
	global_store_dword v[160:161], v126, off
	global_store_dword v[160:161], v110, off offset:1024
	global_store_dword v[160:161], v94, off offset:2048
	global_store_dword v[160:161], v78, off offset:3072
	global_store_dword v[148:149], v62, off
	global_store_dword v[148:149], v46, off offset:1024
	global_store_dword v[148:149], v30, off offset:2048
	global_store_dword v[148:149], v14, off offset:3072
	s_or_b64 exec, exec, s[4:5]
	v_readlane_b32 s95, v250, 45
	v_readlane_b32 s96, v250, 46
	v_readlane_b32 s97, v250, 47
	s_andn2_b64 vcc, exec, s[40:41]
	s_mov_b64 s[4:5], -1
	s_cbranch_vccnz .LBB0_870
	s_andn2_b64 vcc, exec, s[0:1]
	s_cbranch_vccnz .LBB0_869
	s_barrier
	s_branch .LBB0_869

; __device__ __forceinline__ float bflo(unsigned w) { return __uint_as_float(w << 16); }
; __device__ __forceinline__ float bfhi(unsigned w) { return __uint_as_float(w & 0xffff0000u); }
; __device__ __forceinline__ unsigned pk2(float lo, float hi) { f32x2 v = {lo, hi}; bf16x2_t b = __builtin_convertvector(v, bf16x2_t); return __builtin_bit_cast(unsigned, b); }
;     template <int QPR> __device__ __forceinline__ void tailq(int row, int c, const f32x4 v, int) const { quad(row, c, v); }
;     template <int QPR> __device__ __forceinline__ void tailq(int row, int c, const f32x4 v, int) const { quad(row, c, v); }
;     __device__ __forceinline__ float quad(int row, int c, const f32x4 a) const {
;         bf16_t* xp = XB + (size_t)row * D + c;
;         const u32x2 xw = *(const u32x2*)xp;
;         const f32x4 x = (f32x4){bflo(xw.x), bfhi(xw.x), bflo(xw.y), bfhi(xw.y)} + a;
;         u32x2 w; w.x = pk2(x[0], x[1]); w.y = pk2(x[2], x[3]);
;         *(u32x2*)xp = w;
;         return (x[0] * x[0] + x[1] * x[1]) + (x[2] * x[2] + x[3] * x[3]); }
;     template <int QPR> __device__ __forceinline__ void tailq(int row, int c, const f32x4 v, int c0) const {
;         float sq = quad(row, c, v);
; #pragma unroll
;         for (int o = 1; o < QPR; o <<= 1) sq += __shfl_xor(sq, o);
;         if ((threadIdx.x & (QPR - 1)) == 0) ss[(size_t)row * 16 + (c0 >> 6)] = sq; }
;     __device__ __forceinline__ void operator()(const f32x4 (&acc)[2][2][4][2], const pg8::Unit& u, int wr, int wc, int fr, int fq) const {
;         const int row0 = u.pm * 256 + wr * 64 + fr, col0 = u.pn * 256 + wc * 32 + 4 * fq;
; #pragma unroll
;         for (int ai = 0; ai < 2; ++ai)
; #pragma unroll
;             for (int m = 0; m < 4; ++m) { const int row = row0 + ai * 128 + m * 16; float sq = 0.f;
; #pragma unroll
;                 for (int bj = 0; bj < 2; ++bj)
; #pragma unroll
;                     for (int n = 0; n < 2; ++n) { const int c = col0 + bj * 128 + n * 16;
;                         sq += quad(row, c, acc[ai][bj][m][n]); }
;                 sq += __shfl_xor(sq, 16); sq += __shfl_xor(sq, 32);
;                 if (fq == 0) ss[(size_t)row * 16 + u.pn * 4 + wc] = sq; }
.LBB0_1143:
	s_lshl_b32 s60, s30, 2
	s_ashr_i32 s61, s60, 31
	v_lshl_add_u32 v148, s92, 8, v154
	v_lshl_or_b32 v149, s30, 8, v156
	v_and_b32_e32 v151, 4, v156
	v_mul_u32_u24_e32 v151, 6, v151
	v_lshl_add_u32 v150, v149, 1, v151
	v_lshlrev_b32_e32 v152, 11, v148
	v_add_u32_e32 v152, v152, v150
	v_mov_b32_e32 v153, 0
	v_lshl_add_u64 v[158:159], s[12:13], 0, v[152:153]
	v_lshlrev_b32_e32 v152, 6, v148
	v_lshl_add_u64 v[160:161], s[14:15], 0, v[152:153]
	v_lshl_add_u64 v[160:161], s[60:61], 2, v[160:161]
	s_lshl_b32 s30, s86, 2
	v_lshl_add_u64 v[160:161], v[160:161], 0, s[30:31]
	v_mov_b64_e32 v[152:153], v[158:159]
	global_load_dwordx4 v[164:167], v[158:159], off
	global_load_dwordx4 v[168:171], v[158:159], off offset:256
	s_mov_b64 s[4:5], 0x8000
	v_lshl_add_u64 v[158:159], v[158:159], 0, s[4:5]
	global_load_dwordx4 v[172:175], v[158:159], off
	global_load_dwordx4 v[176:179], v[158:159], off offset:256
	s_mov_b64 s[4:5], 0x8000
	v_lshl_add_u64 v[158:159], v[158:159], 0, s[4:5]
	global_load_dwordx4 v[180:183], v[158:159], off
	global_load_dwordx4 v[184:187], v[158:159], off offset:256
	s_mov_b64 s[4:5], 0x8000
	v_lshl_add_u64 v[158:159], v[158:159], 0, s[4:5]
	global_load_dwordx4 v[204:207], v[158:159], off
	global_load_dwordx4 v[208:211], v[158:159], off offset:256
	s_mov_b64 s[4:5], 0x28000
	v_lshl_add_u64 v[158:159], v[158:159], 0, s[4:5]
	global_load_dwordx4 v[212:215], v[158:159], off
	global_load_dwordx4 v[216:219], v[158:159], off offset:256
	s_mov_b64 s[4:5], 0x8000
	v_lshl_add_u64 v[158:159], v[158:159], 0, s[4:5]
	global_load_dwordx4 v[220:223], v[158:159], off
	global_load_dwordx4 v[224:227], v[158:159], off offset:256
	s_mov_b64 s[4:5], 0x8000
	v_lshl_add_u64 v[158:159], v[158:159], 0, s[4:5]
	global_load_dwordx4 v[228:231], v[158:159], off
	global_load_dwordx4 v[232:235], v[158:159], off offset:256
	s_mov_b64 s[4:5], 0x8000
	v_lshl_add_u64 v[158:159], v[158:159], 0, s[4:5]
	global_load_dwordx4 v[236:239], v[158:159], off
	global_load_dwordx4 v[240:243], v[158:159], off offset:256
	v_permlane16_swap_b32 v126, v122
	v_permlane16_swap_b32 v127, v123
	v_permlane16_swap_b32 v128, v124
	v_permlane16_swap_b32 v129, v125
	v_permlane16_swap_b32 v118, v114
	v_permlane16_swap_b32 v119, v115
	v_permlane16_swap_b32 v120, v116
	v_permlane16_swap_b32 v121, v117
	v_permlane16_swap_b32 v110, v106
	v_permlane16_swap_b32 v111, v107
	v_permlane16_swap_b32 v112, v108
	v_permlane16_swap_b32 v113, v109
	v_permlane16_swap_b32 v102, v98
	v_permlane16_swap_b32 v103, v99
	v_permlane16_swap_b32 v104, v100
	v_permlane16_swap_b32 v105, v101
	v_permlane16_swap_b32 v94, v90
	v_permlane16_swap_b32 v95, v91
	v_permlane16_swap_b32 v96, v92
	v_permlane16_swap_b32 v97, v93
	v_permlane16_swap_b32 v86, v82
	v_permlane16_swap_b32 v87, v83
	v_permlane16_swap_b32 v88, v84
	v_permlane16_swap_b32 v89, v85
	v_permlane16_swap_b32 v78, v74
	v_permlane16_swap_b32 v79, v75
	v_permlane16_swap_b32 v80, v76
	v_permlane16_swap_b32 v81, v77
	v_permlane16_swap_b32 v70, v66
	v_permlane16_swap_b32 v71, v67
	v_permlane16_swap_b32 v72, v68
	v_permlane16_swap_b32 v73, v69
	v_permlane16_swap_b32 v62, v58
	v_permlane16_swap_b32 v63, v59
	v_permlane16_swap_b32 v64, v60
	v_permlane16_swap_b32 v65, v61
	v_permlane16_swap_b32 v54, v50
	v_permlane16_swap_b32 v55, v51
	v_permlane16_swap_b32 v56, v52
	v_permlane16_swap_b32 v57, v53
	v_permlane16_swap_b32 v46, v42
	v_permlane16_swap_b32 v47, v43
	v_permlane16_swap_b32 v48, v44
	v_permlane16_swap_b32 v49, v45
	v_permlane16_swap_b32 v38, v34
	v_permlane16_swap_b32 v39, v35
	v_permlane16_swap_b32 v40, v36
	v_permlane16_swap_b32 v41, v37
	v_permlane16_swap_b32 v30, v26
	v_permlane16_swap_b32 v31, v27
	v_permlane16_swap_b32 v32, v28
	v_permlane16_swap_b32 v33, v29
	v_permlane16_swap_b32 v22, v18
	v_permlane16_swap_b32 v23, v19
	v_permlane16_swap_b32 v24, v20
	v_permlane16_swap_b32 v25, v21
	v_permlane16_swap_b32 v14, v10
	v_permlane16_swap_b32 v15, v11
	v_permlane16_swap_b32 v16, v12
	v_permlane16_swap_b32 v17, v13
	v_permlane16_swap_b32 v6, v2
	v_permlane16_swap_b32 v7, v3
	v_permlane16_swap_b32 v8, v4
	v_permlane16_swap_b32 v9, v5
	s_waitcnt vmcnt(15)
	v_lshlrev_b32_e32 v148, 16, v164
	v_and_b32_e32 v149, 0xffff0000, v164
	v_pk_add_f32 v[126:127], v[126:127], v[148:149]
	v_lshlrev_b32_e32 v150, 16, v165
	v_and_b32_e32 v151, 0xffff0000, v165
	v_pk_add_f32 v[128:129], v[128:129], v[150:151]
	v_lshlrev_b32_e32 v148, 16, v166
	v_and_b32_e32 v149, 0xffff0000, v166
	v_pk_add_f32 v[122:123], v[122:123], v[148:149]
	v_lshlrev_b32_e32 v150, 16, v167
	v_and_b32_e32 v151, 0xffff0000, v167
	v_pk_add_f32 v[124:125], v[124:125], v[150:151]
	v_cvt_pk_bf16_f32 v164, v126, v127
	v_cvt_pk_bf16_f32 v165, v128, v129
	v_cvt_pk_bf16_f32 v166, v122, v123
	v_cvt_pk_bf16_f32 v167, v124, v125
	global_store_dwordx4 v[152:153], v[164:167], off
	v_mul_f32_e32 v127, v127, v127
	v_fmac_f32_e32 v127, v126, v126
	v_mul_f32_e32 v126, v129, v129
	v_fmac_f32_e32 v126, v128, v128
	v_add_f32_e32 v126, v127, v126
	v_mul_f32_e32 v123, v123, v123
	v_fmac_f32_e32 v123, v122, v122
	v_mul_f32_e32 v122, v125, v125
	v_fmac_f32_e32 v122, v124, v124
	v_add_f32_e32 v122, v123, v122
	v_add_f32_e32 v126, v126, v122
	s_waitcnt vmcnt(15)
; __device__ __forceinline__ float bflo(unsigned w) { return __uint_as_float(w << 16); }
; __device__ __forceinline__ float bfhi(unsigned w) { return __uint_as_float(w & 0xffff0000u); }
; __device__ __forceinline__ unsigned pk2(float lo, float hi) { f32x2 v = {lo, hi}; bf16x2_t b = __builtin_convertvector(v, bf16x2_t); return __builtin_bit_cast(unsigned, b); }
;     template <int QPR> __device__ __forceinline__ void tailq(int row, int c, const f32x4 v, int) const { quad(row, c, v); }
;     template <int QPR> __device__ __forceinline__ void tailq(int row, int c, const f32x4 v, int) const { quad(row, c, v); }
;     __device__ __forceinline__ float quad(int row, int c, const f32x4 a) const {
;         bf16_t* xp = XB + (size_t)row * D + c;
;         const u32x2 xw = *(const u32x2*)xp;
;         const f32x4 x = (f32x4){bflo(xw.x), bfhi(xw.x), bflo(xw.y), bfhi(xw.y)} + a;
;         u32x2 w; w.x = pk2(x[0], x[1]); w.y = pk2(x[2], x[3]);
;         *(u32x2*)xp = w;
;         return (x[0] * x[0] + x[1] * x[1]) + (x[2] * x[2] + x[3] * x[3]); }
;     template <int QPR> __device__ __forceinline__ void tailq(int row, int c, const f32x4 v, int c0) const {
;         float sq = quad(row, c, v);
; #pragma unroll
;         for (int o = 1; o < QPR; o <<= 1) sq += __shfl_xor(sq, o);
;         if ((threadIdx.x & (QPR - 1)) == 0) ss[(size_t)row * 16 + (c0 >> 6)] = sq; }
;     __device__ __forceinline__ void operator()(const f32x4 (&acc)[2][2][4][2], const pg8::Unit& u, int wr, int wc, int fr, int fq) const {
;         const int row0 = u.pm * 256 + wr * 64 + fr, col0 = u.pn * 256 + wc * 32 + 4 * fq;
; #pragma unroll
;         for (int ai = 0; ai < 2; ++ai)
; #pragma unroll
;             for (int m = 0; m < 4; ++m) { const int row = row0 + ai * 128 + m * 16; float sq = 0.f;
; #pragma unroll
;                 for (int bj = 0; bj < 2; ++bj)
; #pragma unroll
;                     for (int n = 0; n < 2; ++n) { const int c = col0 + bj * 128 + n * 16;
;                         sq += quad(row, c, acc[ai][bj][m][n]); }
;                 sq += __shfl_xor(sq, 16); sq += __shfl_xor(sq, 32);
;                 if (fq == 0) ss[(size_t)row * 16 + u.pn * 4 + wc] = sq; }
	v_lshlrev_b32_e32 v148, 16, v168
	v_and_b32_e32 v149, 0xffff0000, v168
	v_pk_add_f32 v[118:119], v[118:119], v[148:149]
	v_lshlrev_b32_e32 v150, 16, v169
	v_and_b32_e32 v151, 0xffff0000, v169
	v_pk_add_f32 v[120:121], v[120:121], v[150:151]
	v_lshlrev_b32_e32 v148, 16, v170
	v_and_b32_e32 v149, 0xffff0000, v170
	v_pk_add_f32 v[114:115], v[114:115], v[148:149]
	v_lshlrev_b32_e32 v150, 16, v171
	v_and_b32_e32 v151, 0xffff0000, v171
	v_pk_add_f32 v[116:117], v[116:117], v[150:151]
	v_cvt_pk_bf16_f32 v168, v118, v119
	v_cvt_pk_bf16_f32 v169, v120, v121
	v_cvt_pk_bf16_f32 v170, v114, v115
	v_cvt_pk_bf16_f32 v171, v116, v117
	global_store_dwordx4 v[152:153], v[168:171], off offset:256
	s_mov_b64 s[4:5], 0x8000
	v_lshl_add_u64 v[152:153], v[152:153], 0, s[4:5]
	v_mul_f32_e32 v119, v119, v119
	v_fmac_f32_e32 v119, v118, v118
	v_mul_f32_e32 v118, v121, v121
	v_fmac_f32_e32 v118, v120, v120
	v_add_f32_e32 v118, v119, v118
	v_mul_f32_e32 v115, v115, v115
	v_fmac_f32_e32 v115, v114, v114
	v_mul_f32_e32 v114, v117, v117
	v_fmac_f32_e32 v114, v116, v116
	v_add_f32_e32 v114, v115, v114
	v_add_f32_e32 v126, v126, v118
	v_add_f32_e32 v126, v126, v114
	v_mov_b32_e32 v118, v126
	v_mov_b32_e32 v119, v126
	s_nop 1
	v_permlane16_swap_b32 v118, v119
	v_add_f32_e32 v126, v126, v119
	v_mov_b32_e32 v118, v126
	v_mov_b32_e32 v119, v126
	s_nop 1
	v_permlane32_swap_b32 v118, v119
	v_add_f32_e32 v126, v126, v119
	s_waitcnt vmcnt(15)
	v_lshlrev_b32_e32 v148, 16, v172
	v_and_b32_e32 v149, 0xffff0000, v172
	v_pk_add_f32 v[110:111], v[110:111], v[148:149]
	v_lshlrev_b32_e32 v150, 16, v173
	v_and_b32_e32 v151, 0xffff0000, v173
	v_pk_add_f32 v[112:113], v[112:113], v[150:151]
	v_lshlrev_b32_e32 v148, 16, v174
	v_and_b32_e32 v149, 0xffff0000, v174
	v_pk_add_f32 v[106:107], v[106:107], v[148:149]
	v_lshlrev_b32_e32 v150, 16, v175
	v_and_b32_e32 v151, 0xffff0000, v175
	v_pk_add_f32 v[108:109], v[108:109], v[150:151]
	v_cvt_pk_bf16_f32 v172, v110, v111
	v_cvt_pk_bf16_f32 v173, v112, v113
	v_cvt_pk_bf16_f32 v174, v106, v107
	v_cvt_pk_bf16_f32 v175, v108, v109
	global_store_dwordx4 v[152:153], v[172:175], off
	v_mul_f32_e32 v111, v111, v111
	v_fmac_f32_e32 v111, v110, v110
	v_mul_f32_e32 v110, v113, v113
	v_fmac_f32_e32 v110, v112, v112
	v_add_f32_e32 v110, v111, v110
	v_mul_f32_e32 v107, v107, v107
	v_fmac_f32_e32 v107, v106, v106
	v_mul_f32_e32 v106, v109, v109
	v_fmac_f32_e32 v106, v108, v108
	v_add_f32_e32 v106, v107, v106
	v_add_f32_e32 v110, v110, v106
	s_waitcnt vmcnt(15)
	v_lshlrev_b32_e32 v148, 16, v176
	v_and_b32_e32 v149, 0xffff0000, v176
	v_pk_add_f32 v[102:103], v[102:103], v[148:149]
	v_lshlrev_b32_e32 v150, 16, v177
	v_and_b32_e32 v151, 0xffff0000, v177
	v_pk_add_f32 v[104:105], v[104:105], v[150:151]
	v_lshlrev_b32_e32 v148, 16, v178
	v_and_b32_e32 v149, 0xffff0000, v178
	v_pk_add_f32 v[98:99], v[98:99], v[148:149]
	v_lshlrev_b32_e32 v150, 16, v179
	v_and_b32_e32 v151, 0xffff0000, v179
	v_pk_add_f32 v[100:101], v[100:101], v[150:151]
	v_cvt_pk_bf16_f32 v176, v102, v103
	v_cvt_pk_bf16_f32 v177, v104, v105
	v_cvt_pk_bf16_f32 v178, v98, v99
	v_cvt_pk_bf16_f32 v179, v100, v101
	global_store_dwordx4 v[152:153], v[176:179], off offset:256
	s_mov_b64 s[4:5], 0x8000
	v_lshl_add_u64 v[152:153], v[152:153], 0, s[4:5]
	v_mul_f32_e32 v103, v103, v103
	v_fmac_f32_e32 v103, v102, v102
	v_mul_f32_e32 v102, v105, v105
	v_fmac_f32_e32 v102, v104, v104
	v_add_f32_e32 v102, v103, v102
	v_mul_f32_e32 v99, v99, v99
	v_fmac_f32_e32 v99, v98, v98
	v_mul_f32_e32 v98, v101, v101
	v_fmac_f32_e32 v98, v100, v100
	v_add_f32_e32 v98, v99, v98
	v_add_f32_e32 v110, v110, v102
	v_add_f32_e32 v110, v110, v98
	v_mov_b32_e32 v102, v110
	v_mov_b32_e32 v103, v110
	s_nop 1
	v_permlane16_swap_b32 v102, v103
	v_add_f32_e32 v110, v110, v103
	v_mov_b32_e32 v102, v110
	v_mov_b32_e32 v103, v110
	s_nop 1
	v_permlane32_swap_b32 v102, v103
	v_add_f32_e32 v110, v110, v103
	s_waitcnt vmcnt(15)
	v_lshlrev_b32_e32 v148, 16, v180
	v_and_b32_e32 v149, 0xffff0000, v180
	v_pk_add_f32 v[94:95], v[94:95], v[148:149]
	v_lshlrev_b32_e32 v150, 16, v181
	v_and_b32_e32 v151, 0xffff0000, v181
	v_pk_add_f32 v[96:97], v[96:97], v[150:151]
	v_lshlrev_b32_e32 v148, 16, v182
	v_and_b32_e32 v149, 0xffff0000, v182
	v_pk_add_f32 v[90:91], v[90:91], v[148:149]
	v_lshlrev_b32_e32 v150, 16, v183
	v_and_b32_e32 v151, 0xffff0000, v183
	v_pk_add_f32 v[92:93], v[92:93], v[150:151]
	v_cvt_pk_bf16_f32 v180, v94, v95
	v_cvt_pk_bf16_f32 v181, v96, v97
	v_cvt_pk_bf16_f32 v182, v90, v91
	v_cvt_pk_bf16_f32 v183, v92, v93
	global_store_dwordx4 v[152:153], v[180:183], off
	v_mul_f32_e32 v95, v95, v95
	v_fmac_f32_e32 v95, v94, v94
	v_mul_f32_e32 v94, v97, v97
	v_fmac_f32_e32 v94, v96, v96
	v_add_f32_e32 v94, v95, v94
	v_mul_f32_e32 v91, v91, v91
	v_fmac_f32_e32 v91, v90, v90
	v_mul_f32_e32 v90, v93, v93
	v_fmac_f32_e32 v90, v92, v92
	v_add_f32_e32 v90, v91, v90
	v_add_f32_e32 v94, v94, v90
	s_waitcnt vmcnt(15)
	v_lshlrev_b32_e32 v148, 16, v184
	v_and_b32_e32 v149, 0xffff0000, v184
	v_pk_add_f32 v[86:87], v[86:87], v[148:149]
	v_lshlrev_b32_e32 v150, 16, v185
	v_and_b32_e32 v151, 0xffff0000, v185
	v_pk_add_f32 v[88:89], v[88:89], v[150:151]
	v_lshlrev_b32_e32 v148, 16, v186
	v_and_b32_e32 v149, 0xffff0000, v186
	v_pk_add_f32 v[82:83], v[82:83], v[148:149]
	v_lshlrev_b32_e32 v150, 16, v187
	v_and_b32_e32 v151, 0xffff0000, v187
	v_pk_add_f32 v[84:85], v[84:85], v[150:151]
	v_cvt_pk_bf16_f32 v184, v86, v87
	v_cvt_pk_bf16_f32 v185, v88, v89
	v_cvt_pk_bf16_f32 v186, v82, v83
	v_cvt_pk_bf16_f32 v187, v84, v85
	global_store_dwordx4 v[152:153], v[184:187], off offset:256
	s_mov_b64 s[4:5], 0x8000
	v_lshl_add_u64 v[152:153], v[152:153], 0, s[4:5]
	v_mul_f32_e32 v87, v87, v87
	v_fmac_f32_e32 v87, v86, v86
	v_mul_f32_e32 v86, v89, v89
	v_fmac_f32_e32 v86, v88, v88
	v_add_f32_e32 v86, v87, v86
	v_mul_f32_e32 v83, v83, v83
	v_fmac_f32_e32 v83, v82, v82
	v_mul_f32_e32 v82, v85, v85
	v_fmac_f32_e32 v82, v84, v84
	v_add_f32_e32 v82, v83, v82
	v_add_f32_e32 v94, v94, v86
	v_add_f32_e32 v94, v94, v82
	v_mov_b32_e32 v86, v94
	v_mov_b32_e32 v87, v94
	s_nop 1
	v_permlane16_swap_b32 v86, v87
	v_add_f32_e32 v94, v94, v87
	v_mov_b32_e32 v86, v94
	v_mov_b32_e32 v87, v94
	s_nop 1
	v_permlane32_swap_b32 v86, v87
	v_add_f32_e32 v94, v94, v87
	s_waitcnt vmcnt(15)
; __device__ __forceinline__ float bflo(unsigned w) { return __uint_as_float(w << 16); }
; __device__ __forceinline__ float bfhi(unsigned w) { return __uint_as_float(w & 0xffff0000u); }
; __device__ __forceinline__ unsigned pk2(float lo, float hi) { f32x2 v = {lo, hi}; bf16x2_t b = __builtin_convertvector(v, bf16x2_t); return __builtin_bit_cast(unsigned, b); }
;     template <int QPR> __device__ __forceinline__ void tailq(int row, int c, const f32x4 v, int) const { quad(row, c, v); }
;     template <int QPR> __device__ __forceinline__ void tailq(int row, int c, const f32x4 v, int) const { quad(row, c, v); }
;     __device__ __forceinline__ float quad(int row, int c, const f32x4 a) const {
;         bf16_t* xp = XB + (size_t)row * D + c;
;         const u32x2 xw = *(const u32x2*)xp;
;         const f32x4 x = (f32x4){bflo(xw.x), bfhi(xw.x), bflo(xw.y), bfhi(xw.y)} + a;
;         u32x2 w; w.x = pk2(x[0], x[1]); w.y = pk2(x[2], x[3]);
;         *(u32x2*)xp = w;
;         return (x[0] * x[0] + x[1] * x[1]) + (x[2] * x[2] + x[3] * x[3]); }
;     template <int QPR> __device__ __forceinline__ void tailq(int row, int c, const f32x4 v, int c0) const {
;         float sq = quad(row, c, v);
; #pragma unroll
;         for (int o = 1; o < QPR; o <<= 1) sq += __shfl_xor(sq, o);
;         if ((threadIdx.x & (QPR - 1)) == 0) ss[(size_t)row * 16 + (c0 >> 6)] = sq; }
;     __device__ __forceinline__ void operator()(const f32x4 (&acc)[2][2][4][2], const pg8::Unit& u, int wr, int wc, int fr, int fq) const {
;         const int row0 = u.pm * 256 + wr * 64 + fr, col0 = u.pn * 256 + wc * 32 + 4 * fq;
; #pragma unroll
;         for (int ai = 0; ai < 2; ++ai)
; #pragma unroll
;             for (int m = 0; m < 4; ++m) { const int row = row0 + ai * 128 + m * 16; float sq = 0.f;
; #pragma unroll
;                 for (int bj = 0; bj < 2; ++bj)
; #pragma unroll
;                     for (int n = 0; n < 2; ++n) { const int c = col0 + bj * 128 + n * 16;
;                         sq += quad(row, c, acc[ai][bj][m][n]); }
;                 sq += __shfl_xor(sq, 16); sq += __shfl_xor(sq, 32);
;                 if (fq == 0) ss[(size_t)row * 16 + u.pn * 4 + wc] = sq; }
	v_lshlrev_b32_e32 v148, 16, v204
	v_and_b32_e32 v149, 0xffff0000, v204
	v_pk_add_f32 v[78:79], v[78:79], v[148:149]
	v_lshlrev_b32_e32 v150, 16, v205
	v_and_b32_e32 v151, 0xffff0000, v205
	v_pk_add_f32 v[80:81], v[80:81], v[150:151]
	v_lshlrev_b32_e32 v148, 16, v206
	v_and_b32_e32 v149, 0xffff0000, v206
	v_pk_add_f32 v[74:75], v[74:75], v[148:149]
	v_lshlrev_b32_e32 v150, 16, v207
	v_and_b32_e32 v151, 0xffff0000, v207
	v_pk_add_f32 v[76:77], v[76:77], v[150:151]
	v_cvt_pk_bf16_f32 v204, v78, v79
	v_cvt_pk_bf16_f32 v205, v80, v81
	v_cvt_pk_bf16_f32 v206, v74, v75
	v_cvt_pk_bf16_f32 v207, v76, v77
	global_store_dwordx4 v[152:153], v[204:207], off
	v_mul_f32_e32 v79, v79, v79
	v_fmac_f32_e32 v79, v78, v78
	v_mul_f32_e32 v78, v81, v81
	v_fmac_f32_e32 v78, v80, v80
	v_add_f32_e32 v78, v79, v78
	v_mul_f32_e32 v75, v75, v75
	v_fmac_f32_e32 v75, v74, v74
	v_mul_f32_e32 v74, v77, v77
	v_fmac_f32_e32 v74, v76, v76
	v_add_f32_e32 v74, v75, v74
	v_add_f32_e32 v78, v78, v74
	s_waitcnt vmcnt(15)
	v_lshlrev_b32_e32 v148, 16, v208
	v_and_b32_e32 v149, 0xffff0000, v208
	v_pk_add_f32 v[70:71], v[70:71], v[148:149]
	v_lshlrev_b32_e32 v150, 16, v209
	v_and_b32_e32 v151, 0xffff0000, v209
	v_pk_add_f32 v[72:73], v[72:73], v[150:151]
	v_lshlrev_b32_e32 v148, 16, v210
	v_and_b32_e32 v149, 0xffff0000, v210
	v_pk_add_f32 v[66:67], v[66:67], v[148:149]
	v_lshlrev_b32_e32 v150, 16, v211
	v_and_b32_e32 v151, 0xffff0000, v211
	v_pk_add_f32 v[68:69], v[68:69], v[150:151]
	v_cvt_pk_bf16_f32 v208, v70, v71
	v_cvt_pk_bf16_f32 v209, v72, v73
	v_cvt_pk_bf16_f32 v210, v66, v67
	v_cvt_pk_bf16_f32 v211, v68, v69
	global_store_dwordx4 v[152:153], v[208:211], off offset:256
	s_mov_b64 s[4:5], 0x28000
	v_lshl_add_u64 v[152:153], v[152:153], 0, s[4:5]
	v_mul_f32_e32 v71, v71, v71
	v_fmac_f32_e32 v71, v70, v70
	v_mul_f32_e32 v70, v73, v73
	v_fmac_f32_e32 v70, v72, v72
	v_add_f32_e32 v70, v71, v70
	v_mul_f32_e32 v67, v67, v67
	v_fmac_f32_e32 v67, v66, v66
	v_mul_f32_e32 v66, v69, v69
	v_fmac_f32_e32 v66, v68, v68
	v_add_f32_e32 v66, v67, v66
	v_add_f32_e32 v78, v78, v70
	v_add_f32_e32 v78, v78, v66
	v_mov_b32_e32 v70, v78
	v_mov_b32_e32 v71, v78
	s_nop 1
	v_permlane16_swap_b32 v70, v71
	v_add_f32_e32 v78, v78, v71
	v_mov_b32_e32 v70, v78
	v_mov_b32_e32 v71, v78
	s_nop 1
	v_permlane32_swap_b32 v70, v71
	v_add_f32_e32 v78, v78, v71
	s_waitcnt vmcnt(15)
	v_lshlrev_b32_e32 v148, 16, v212
	v_and_b32_e32 v149, 0xffff0000, v212
	v_pk_add_f32 v[62:63], v[62:63], v[148:149]
	v_lshlrev_b32_e32 v150, 16, v213
	v_and_b32_e32 v151, 0xffff0000, v213
	v_pk_add_f32 v[64:65], v[64:65], v[150:151]
	v_lshlrev_b32_e32 v148, 16, v214
	v_and_b32_e32 v149, 0xffff0000, v214
	v_pk_add_f32 v[58:59], v[58:59], v[148:149]
	v_lshlrev_b32_e32 v150, 16, v215
	v_and_b32_e32 v151, 0xffff0000, v215
	v_pk_add_f32 v[60:61], v[60:61], v[150:151]
	v_cvt_pk_bf16_f32 v212, v62, v63
	v_cvt_pk_bf16_f32 v213, v64, v65
	v_cvt_pk_bf16_f32 v214, v58, v59
	v_cvt_pk_bf16_f32 v215, v60, v61
	global_store_dwordx4 v[152:153], v[212:215], off
	v_mul_f32_e32 v63, v63, v63
	v_fmac_f32_e32 v63, v62, v62
	v_mul_f32_e32 v62, v65, v65
	v_fmac_f32_e32 v62, v64, v64
	v_add_f32_e32 v62, v63, v62
	v_mul_f32_e32 v59, v59, v59
	v_fmac_f32_e32 v59, v58, v58
	v_mul_f32_e32 v58, v61, v61
	v_fmac_f32_e32 v58, v60, v60
	v_add_f32_e32 v58, v59, v58
	v_add_f32_e32 v62, v62, v58
	s_waitcnt vmcnt(15)
	v_lshlrev_b32_e32 v148, 16, v216
	v_and_b32_e32 v149, 0xffff0000, v216
	v_pk_add_f32 v[54:55], v[54:55], v[148:149]
	v_lshlrev_b32_e32 v150, 16, v217
	v_and_b32_e32 v151, 0xffff0000, v217
	v_pk_add_f32 v[56:57], v[56:57], v[150:151]
	v_lshlrev_b32_e32 v148, 16, v218
	v_and_b32_e32 v149, 0xffff0000, v218
	v_pk_add_f32 v[50:51], v[50:51], v[148:149]
	v_lshlrev_b32_e32 v150, 16, v219
	v_and_b32_e32 v151, 0xffff0000, v219
	v_pk_add_f32 v[52:53], v[52:53], v[150:151]
	v_cvt_pk_bf16_f32 v216, v54, v55
	v_cvt_pk_bf16_f32 v217, v56, v57
	v_cvt_pk_bf16_f32 v218, v50, v51
	v_cvt_pk_bf16_f32 v219, v52, v53
	global_store_dwordx4 v[152:153], v[216:219], off offset:256
	s_mov_b64 s[4:5], 0x8000
	v_lshl_add_u64 v[152:153], v[152:153], 0, s[4:5]
	v_mul_f32_e32 v55, v55, v55
	v_fmac_f32_e32 v55, v54, v54
	v_mul_f32_e32 v54, v57, v57
	v_fmac_f32_e32 v54, v56, v56
	v_add_f32_e32 v54, v55, v54
	v_mul_f32_e32 v51, v51, v51
	v_fmac_f32_e32 v51, v50, v50
	v_mul_f32_e32 v50, v53, v53
	v_fmac_f32_e32 v50, v52, v52
	v_add_f32_e32 v50, v51, v50
	v_add_f32_e32 v62, v62, v54
	v_add_f32_e32 v62, v62, v50
	v_mov_b32_e32 v54, v62
	v_mov_b32_e32 v55, v62
	s_nop 1
	v_permlane16_swap_b32 v54, v55
	v_add_f32_e32 v62, v62, v55
	v_mov_b32_e32 v54, v62
	v_mov_b32_e32 v55, v62
	s_nop 1
	v_permlane32_swap_b32 v54, v55
	v_add_f32_e32 v62, v62, v55
	s_waitcnt vmcnt(15)
	v_lshlrev_b32_e32 v148, 16, v220
	v_and_b32_e32 v149, 0xffff0000, v220
	v_pk_add_f32 v[46:47], v[46:47], v[148:149]
	v_lshlrev_b32_e32 v150, 16, v221
	v_and_b32_e32 v151, 0xffff0000, v221
	v_pk_add_f32 v[48:49], v[48:49], v[150:151]
	v_lshlrev_b32_e32 v148, 16, v222
	v_and_b32_e32 v149, 0xffff0000, v222
	v_pk_add_f32 v[42:43], v[42:43], v[148:149]
	v_lshlrev_b32_e32 v150, 16, v223
	v_and_b32_e32 v151, 0xffff0000, v223
	v_pk_add_f32 v[44:45], v[44:45], v[150:151]
	v_cvt_pk_bf16_f32 v220, v46, v47
	v_cvt_pk_bf16_f32 v221, v48, v49
	v_cvt_pk_bf16_f32 v222, v42, v43
	v_cvt_pk_bf16_f32 v223, v44, v45
	global_store_dwordx4 v[152:153], v[220:223], off
	v_mul_f32_e32 v47, v47, v47
	v_fmac_f32_e32 v47, v46, v46
	v_mul_f32_e32 v46, v49, v49
	v_fmac_f32_e32 v46, v48, v48
	v_add_f32_e32 v46, v47, v46
	v_mul_f32_e32 v43, v43, v43
	v_fmac_f32_e32 v43, v42, v42
	v_mul_f32_e32 v42, v45, v45
	v_fmac_f32_e32 v42, v44, v44
	v_add_f32_e32 v42, v43, v42
	v_add_f32_e32 v46, v46, v42
	s_waitcnt vmcnt(15)
; __device__ __forceinline__ float bflo(unsigned w) { return __uint_as_float(w << 16); }
; __device__ __forceinline__ float bfhi(unsigned w) { return __uint_as_float(w & 0xffff0000u); }
; __device__ __forceinline__ unsigned pk2(float lo, float hi) { f32x2 v = {lo, hi}; bf16x2_t b = __builtin_convertvector(v, bf16x2_t); return __builtin_bit_cast(unsigned, b); }
;     template <int QPR> __device__ __forceinline__ void tailq(int row, int c, const f32x4 v, int) const { quad(row, c, v); }
;     template <int QPR> __device__ __forceinline__ void tailq(int row, int c, const f32x4 v, int) const { quad(row, c, v); }
;     __device__ __forceinline__ float quad(int row, int c, const f32x4 a) const {
;         bf16_t* xp = XB + (size_t)row * D + c;
;         const u32x2 xw = *(const u32x2*)xp;
;         const f32x4 x = (f32x4){bflo(xw.x), bfhi(xw.x), bflo(xw.y), bfhi(xw.y)} + a;
;         u32x2 w; w.x = pk2(x[0], x[1]); w.y = pk2(x[2], x[3]);
;         *(u32x2*)xp = w;
;         return (x[0] * x[0] + x[1] * x[1]) + (x[2] * x[2] + x[3] * x[3]); }
;     template <int QPR> __device__ __forceinline__ void tailq(int row, int c, const f32x4 v, int c0) const {
;         float sq = quad(row, c, v);
; #pragma unroll
;         for (int o = 1; o < QPR; o <<= 1) sq += __shfl_xor(sq, o);
;         if ((threadIdx.x & (QPR - 1)) == 0) ss[(size_t)row * 16 + (c0 >> 6)] = sq; }
;     __device__ __forceinline__ void operator()(const f32x4 (&acc)[2][2][4][2], const pg8::Unit& u, int wr, int wc, int fr, int fq) const {
;         const int row0 = u.pm * 256 + wr * 64 + fr, col0 = u.pn * 256 + wc * 32 + 4 * fq;
; #pragma unroll
;         for (int ai = 0; ai < 2; ++ai)
; #pragma unroll
;             for (int m = 0; m < 4; ++m) { const int row = row0 + ai * 128 + m * 16; float sq = 0.f;
; #pragma unroll
;                 for (int bj = 0; bj < 2; ++bj)
; #pragma unroll
;                     for (int n = 0; n < 2; ++n) { const int c = col0 + bj * 128 + n * 16;
;                         sq += quad(row, c, acc[ai][bj][m][n]); }
;                 sq += __shfl_xor(sq, 16); sq += __shfl_xor(sq, 32);
;                 if (fq == 0) ss[(size_t)row * 16 + u.pn * 4 + wc] = sq; }
	v_lshlrev_b32_e32 v148, 16, v224
	v_and_b32_e32 v149, 0xffff0000, v224
	v_pk_add_f32 v[38:39], v[38:39], v[148:149]
	v_lshlrev_b32_e32 v150, 16, v225
	v_and_b32_e32 v151, 0xffff0000, v225
	v_pk_add_f32 v[40:41], v[40:41], v[150:151]
	v_lshlrev_b32_e32 v148, 16, v226
	v_and_b32_e32 v149, 0xffff0000, v226
	v_pk_add_f32 v[34:35], v[34:35], v[148:149]
	v_lshlrev_b32_e32 v150, 16, v227
	v_and_b32_e32 v151, 0xffff0000, v227
	v_pk_add_f32 v[36:37], v[36:37], v[150:151]
	v_cvt_pk_bf16_f32 v224, v38, v39
	v_cvt_pk_bf16_f32 v225, v40, v41
	v_cvt_pk_bf16_f32 v226, v34, v35
	v_cvt_pk_bf16_f32 v227, v36, v37
	global_store_dwordx4 v[152:153], v[224:227], off offset:256
	s_mov_b64 s[4:5], 0x8000
	v_lshl_add_u64 v[152:153], v[152:153], 0, s[4:5]
	v_mul_f32_e32 v39, v39, v39
	v_fmac_f32_e32 v39, v38, v38
	v_mul_f32_e32 v38, v41, v41
	v_fmac_f32_e32 v38, v40, v40
	v_add_f32_e32 v38, v39, v38
	v_mul_f32_e32 v35, v35, v35
	v_fmac_f32_e32 v35, v34, v34
	v_mul_f32_e32 v34, v37, v37
	v_fmac_f32_e32 v34, v36, v36
	v_add_f32_e32 v34, v35, v34
	v_add_f32_e32 v46, v46, v38
	v_add_f32_e32 v46, v46, v34
	v_mov_b32_e32 v38, v46
	v_mov_b32_e32 v39, v46
	s_nop 1
	v_permlane16_swap_b32 v38, v39
	v_add_f32_e32 v46, v46, v39
	v_mov_b32_e32 v38, v46
	v_mov_b32_e32 v39, v46
	s_nop 1
	v_permlane32_swap_b32 v38, v39
	v_add_f32_e32 v46, v46, v39
	s_waitcnt vmcnt(15)
	v_lshlrev_b32_e32 v148, 16, v228
	v_and_b32_e32 v149, 0xffff0000, v228
	v_pk_add_f32 v[30:31], v[30:31], v[148:149]
	v_lshlrev_b32_e32 v150, 16, v229
	v_and_b32_e32 v151, 0xffff0000, v229
	v_pk_add_f32 v[32:33], v[32:33], v[150:151]
	v_lshlrev_b32_e32 v148, 16, v230
	v_and_b32_e32 v149, 0xffff0000, v230
	v_pk_add_f32 v[26:27], v[26:27], v[148:149]
	v_lshlrev_b32_e32 v150, 16, v231
	v_and_b32_e32 v151, 0xffff0000, v231
	v_pk_add_f32 v[28:29], v[28:29], v[150:151]
	v_cvt_pk_bf16_f32 v228, v30, v31
	v_cvt_pk_bf16_f32 v229, v32, v33
	v_cvt_pk_bf16_f32 v230, v26, v27
	v_cvt_pk_bf16_f32 v231, v28, v29
	global_store_dwordx4 v[152:153], v[228:231], off
	v_mul_f32_e32 v31, v31, v31
	v_fmac_f32_e32 v31, v30, v30
	v_mul_f32_e32 v30, v33, v33
	v_fmac_f32_e32 v30, v32, v32
	v_add_f32_e32 v30, v31, v30
	v_mul_f32_e32 v27, v27, v27
	v_fmac_f32_e32 v27, v26, v26
	v_mul_f32_e32 v26, v29, v29
	v_fmac_f32_e32 v26, v28, v28
	v_add_f32_e32 v26, v27, v26
	v_add_f32_e32 v30, v30, v26
	s_waitcnt vmcnt(15)
	v_lshlrev_b32_e32 v148, 16, v232
	v_and_b32_e32 v149, 0xffff0000, v232
	v_pk_add_f32 v[22:23], v[22:23], v[148:149]
	v_lshlrev_b32_e32 v150, 16, v233
	v_and_b32_e32 v151, 0xffff0000, v233
	v_pk_add_f32 v[24:25], v[24:25], v[150:151]
	v_lshlrev_b32_e32 v148, 16, v234
	v_and_b32_e32 v149, 0xffff0000, v234
	v_pk_add_f32 v[18:19], v[18:19], v[148:149]
	v_lshlrev_b32_e32 v150, 16, v235
	v_and_b32_e32 v151, 0xffff0000, v235
	v_pk_add_f32 v[20:21], v[20:21], v[150:151]
	v_cvt_pk_bf16_f32 v232, v22, v23
	v_cvt_pk_bf16_f32 v233, v24, v25
	v_cvt_pk_bf16_f32 v234, v18, v19
	v_cvt_pk_bf16_f32 v235, v20, v21
	global_store_dwordx4 v[152:153], v[232:235], off offset:256
	s_mov_b64 s[4:5], 0x8000
	v_lshl_add_u64 v[152:153], v[152:153], 0, s[4:5]
	v_mul_f32_e32 v23, v23, v23
	v_fmac_f32_e32 v23, v22, v22
	v_mul_f32_e32 v22, v25, v25
	v_fmac_f32_e32 v22, v24, v24
	v_add_f32_e32 v22, v23, v22
	v_mul_f32_e32 v19, v19, v19
	v_fmac_f32_e32 v19, v18, v18
	v_mul_f32_e32 v18, v21, v21
	v_fmac_f32_e32 v18, v20, v20
	v_add_f32_e32 v18, v19, v18
	v_add_f32_e32 v30, v30, v22
	v_add_f32_e32 v30, v30, v18
	v_mov_b32_e32 v22, v30
	v_mov_b32_e32 v23, v30
	s_nop 1
	v_permlane16_swap_b32 v22, v23
	v_add_f32_e32 v30, v30, v23
	v_mov_b32_e32 v22, v30
	v_mov_b32_e32 v23, v30
	s_nop 1
	v_permlane32_swap_b32 v22, v23
	v_add_f32_e32 v30, v30, v23
	s_waitcnt vmcnt(15)
	v_lshlrev_b32_e32 v148, 16, v236
	v_and_b32_e32 v149, 0xffff0000, v236
	v_pk_add_f32 v[14:15], v[14:15], v[148:149]
	v_lshlrev_b32_e32 v150, 16, v237
	v_and_b32_e32 v151, 0xffff0000, v237
	v_pk_add_f32 v[16:17], v[16:17], v[150:151]
	v_lshlrev_b32_e32 v148, 16, v238
	v_and_b32_e32 v149, 0xffff0000, v238
	v_pk_add_f32 v[10:11], v[10:11], v[148:149]
	v_lshlrev_b32_e32 v150, 16, v239
	v_and_b32_e32 v151, 0xffff0000, v239
	v_pk_add_f32 v[12:13], v[12:13], v[150:151]
	v_cvt_pk_bf16_f32 v236, v14, v15
	v_cvt_pk_bf16_f32 v237, v16, v17
	v_cvt_pk_bf16_f32 v238, v10, v11
	v_cvt_pk_bf16_f32 v239, v12, v13
	global_store_dwordx4 v[152:153], v[236:239], off
	v_mul_f32_e32 v15, v15, v15
	v_fmac_f32_e32 v15, v14, v14
	v_mul_f32_e32 v14, v17, v17
	v_fmac_f32_e32 v14, v16, v16
	v_add_f32_e32 v14, v15, v14
	v_mul_f32_e32 v11, v11, v11
	v_fmac_f32_e32 v11, v10, v10
	v_mul_f32_e32 v10, v13, v13
	v_fmac_f32_e32 v10, v12, v12
	v_add_f32_e32 v10, v11, v10
	v_add_f32_e32 v14, v14, v10
	s_waitcnt vmcnt(15)
	v_lshlrev_b32_e32 v148, 16, v240
	v_and_b32_e32 v149, 0xffff0000, v240
	v_pk_add_f32 v[6:7], v[6:7], v[148:149]
	v_lshlrev_b32_e32 v150, 16, v241
	v_and_b32_e32 v151, 0xffff0000, v241
	v_pk_add_f32 v[8:9], v[8:9], v[150:151]
	v_lshlrev_b32_e32 v148, 16, v242
	v_and_b32_e32 v149, 0xffff0000, v242
	v_pk_add_f32 v[2:3], v[2:3], v[148:149]
	v_lshlrev_b32_e32 v150, 16, v243
	v_and_b32_e32 v151, 0xffff0000, v243
	v_pk_add_f32 v[4:5], v[4:5], v[150:151]
	v_cvt_pk_bf16_f32 v240, v6, v7
	v_cvt_pk_bf16_f32 v241, v8, v9
	v_cvt_pk_bf16_f32 v242, v2, v3
	v_cvt_pk_bf16_f32 v243, v4, v5
	global_store_dwordx4 v[152:153], v[240:243], off offset:256
	v_mul_f32_e32 v7, v7, v7
	v_fmac_f32_e32 v7, v6, v6
	v_mul_f32_e32 v6, v9, v9
	v_fmac_f32_e32 v6, v8, v8
	v_add_f32_e32 v6, v7, v6
	v_mul_f32_e32 v3, v3, v3
	v_fmac_f32_e32 v3, v2, v2
	v_mul_f32_e32 v2, v5, v5
	v_fmac_f32_e32 v2, v4, v4
	v_add_f32_e32 v2, v3, v2
	v_add_f32_e32 v14, v14, v6
	v_add_f32_e32 v14, v14, v2
	v_mov_b32_e32 v6, v14
	v_mov_b32_e32 v7, v14
	s_nop 1
	v_permlane16_swap_b32 v6, v7
	v_add_f32_e32 v14, v14, v7
	v_mov_b32_e32 v6, v14
	v_mov_b32_e32 v7, v14
	s_nop 1
	v_permlane32_swap_b32 v6, v7
	v_add_f32_e32 v14, v14, v7
	s_mov_b64 s[4:5], 0x2000
	v_lshl_add_u64 v[148:149], v[160:161], 0, s[4:5]
	s_and_saveexec_b64 s[4:5], s[38:39]
	global_store_dword v[160:161], v126, off
	global_store_dword v[160:161], v110, off offset:1024
	global_store_dword v[160:161], v94, off offset:2048
	global_store_dword v[160:161], v78, off offset:3072
	global_store_dword v[148:149], v62, off
	global_store_dword v[148:149], v46, off offset:1024
	global_store_dword v[148:149], v30, off offset:2048
	global_store_dword v[148:149], v14, off offset:3072
	s_or_b64 exec, exec, s[4:5]
	v_readlane_b32 s95, v250, 45
	v_readlane_b32 s96, v250, 46
	v_readlane_b32 s97, v250, 47
	s_and_b64 vcc, exec, s[40:41]
	s_mov_b64 s[4:5], -1
	s_cbranch_vccnz .LBB0_1128
	s_andn2_b64 vcc, exec, s[52:53]
	s_cbranch_vccnz .LBB0_1127
	s_barrier
	s_branch .LBB0_1127
